# MoBA prologue v2: kbar + gate q-row loads issued before the K/V DMAs, gate runs under counted vmcnt(4) while DMAs fly
# speedup vs baseline: 1.0156x; 1.0017x over previous
; template<int THRL,int MODE,int DM,bool DRY=false> __device__ __forceinline__ void attn_unit(int b,int h,int qb,const bf16*Q,const bf16*__restrict__ K,const bf16*__restrict__ V,bf16*O,const bf16*__restrict__ Z,const float*__restrict__ XP,const int*__restrict__ TS,volatile unsigned*lw,unsigned nxt,cha ...
;     ...
;   const bf16*Qw=Q+(rowbase+q0+wid*QBLK)*DM+h*D;
;   bf16x8 qr[4];
;   #pragma unroll
;   for(int d0=0;d0<4;++d0)qr[d0]=*reinterpret_cast<const bf16x8*>(&Qw[(long)r32*DM+d0*16+hi*8]);
;   const bf16*Kh=K+rowbase*DM+h*D,*Vh=V+rowbase*DM+h*D;
;   const unsigned lds0=(unsigned)(uintptr_t)shm;
;   float*wsf=(float*)(shm+LDS_WS)+wid*64;
;   const bf16*ksrc_=Kh+(long)lane*DM+wid*8; int tskip=0,fixedref=0; const bf16*ksrc=ksrc_;
;   const bf16*vsrc_=Vh+(long)(16*(wid&3)+(lane>>2))*DM+(wid>>2)*32+(lane&3)*8; const bf16*vsrc=vsrc_;
;   const unsigned kdst=lds0+LDS_K+wid*1024, vdst=lds0+LDS_V+wid*1024;
;     ...
;   const int vb0=(int)(lds0+LDS_V)+((lane>>4)&1)*32+(lane&3)*8+(4*hi+((lane&15)>>2))*64;
;   const char*Kbase=shm+LDS_K; bf16x8 kf[8];
;   const lds_cptr shm3=(lds_cptr)shm; const lds_cptr kp0=shm3+LDS_K+hi*1024+r32*16; const lds_cptr vp0=shm3+LDS_V+((lane>>4)&1)*32+(lane&3)*8+(4*hi+((lane&15)>>2))*64;
;   int NT=(q0+QB)/KVBLK;
;   const int qrel=wid*QBLK+r32;
;   unsigned sel=0u;
;   if constexpr(MODE==1){
;     { const int tsv=__builtin_amdgcn_readfirstlane(TS[qb]); tskip=tsv&0xffff; fixedref=(tsv>>16)&1; }
;     ksrc=ksrc_+(long)tskip*KVBLK*DM; vsrc=vsrc_+(long)tskip*KVBLK*DM; NT-=tskip;
;   }
;   const lds_cptr fsl=(lds_cptr)shm+XOFF+16*hi+tskip*256;
;     ...
;   DMA_K(0,0);DMA_V(0,0);DMA_K(1,SLOTB);
;   float mhat=0.f,l_reg=0.f;f32x16 o[2];o[0]=f32x16{};o[1]=f32x16{};f32x16 negm=f32x16{}; if constexpr(MODE==0){asm volatile("":"+v"(negm));}
;     ...
;   const f32x16 czero_=f32x16{};
;     ...
;   bool resc=false;
;     ...
;   f32x16 pA0,pA1,pB0,pB1;
;   int sl_prev=0,sl_cur=0,sl_next=SLOTB;
;     ...
;   DMA_K(2,2*SLOTB);
;   if constexpr(MODE==1){ float*fs=(float*)(shm+XOFF); for(int i=tid+64*tskip;i<q0+QB;i+=NW*64)fs[i]=XP[i]; }
;   if constexpr(MODE==0){
;     float*kbs=(float*)(shm+XOFF); unsigned*sm=(unsigned*)(shm+XOFF+2048);
;     kbs[tid]=XP[tid];
;     asm volatile("s_waitcnt vmcnt(0) lgkmcnt(0)\n\ts_barrier":::"memory");
;     if(tid<QB){ unsigned m=(1u<<qb)-1u;
;       if(qb>3){ const bf16*qp=Q+(rowbase+q0+tid)*DM+h*D; float g[8];
;         _Pragma("unroll") for(int n=0;n<8;++n)g[n]=0.f;
.LBB0_894:
	s_or_b64 exec, exec, s[8:9]
	s_ashr_i32 s8, s10, 31
	s_lshr_b32 s8, s8, 25
	s_add_i32 s8, s10, s8
	s_ashr_i32 s9, s8, 7
	s_and_b32 s8, s8, 0xffffff80
	s_sub_i32 s64, s10, s8
	s_ashr_i32 s65, s64, 31
	s_sub_i32 s92, 0, s9
	s_sub_i32 s95, 7, s9
	s_ashr_i32 s70, s64, 4
	s_lshl_b64 s[8:9], s[64:65], 11
	s_add_u32 s10, s26, s8
	v_mov_b32_e32 v224, v220
	s_addc_u32 s11, s45, s9
	s_ashr_i32 s71, s70, 31
	v_readfirstlane_b32 s93, v224
	s_ashr_i32 s65, s93, 6
	s_lshl_b64 s[8:9], s[70:71], 11
	s_lshl_b32 s94, s95, 8
	s_add_u32 s8, s8, s94
	s_addc_u32 s9, s9, 0
	s_lshl_b32 s96, s65, 5
	s_ashr_i32 s12, s96, 31
	s_add_u32 s14, s8, s96
	s_addc_u32 s12, s9, s12
	s_mulk_i32 s12, 0x1a00
	s_mul_hi_u32 s13, s14, 0x1a00
	s_add_i32 s13, s13, s12
	s_mul_i32 s12, s14, 0x1a00
	s_lshl_b64 s[60:61], s[12:13], 1
	s_add_u32 s12, s28, s60
	s_addc_u32 s13, s29, s61
	s_lshl_b32 s14, s64, 6
	s_and_b32 s14, s14, 0x3c0
	s_lshl_b32 s62, s14, 1
	s_add_u32 s58, s12, s62
	s_addc_u32 s59, s13, 0
	s_mul_i32 s15, s70, 0x1a00000
	s_mul_hi_i32 s14, s70, 0x1a00000
	s_add_u32 s12, s47, s15
	v_and_b32_e32 v237, 31, v224
	s_addc_u32 s13, s84, s14
	v_mul_u32_u24_e32 v16, 0x1a00, v237
	s_add_u32 s12, s12, s62
	v_bfe_u32 v238, v224, 5, 1
	v_lshlrev_b32_e32 v16, 1, v16
	s_addc_u32 s13, s13, 0
	v_lshl_or_b32 v222, v238, 4, v16
	s_add_u32 s15, s85, s15
	v_and_b32_e32 v239, 63, v224
	v_lshl_add_u64 v[16:17], s[58:59], 0, v[222:223]
	s_addc_u32 s16, s86, s14
	flat_load_dwordx4 v[156:159], v[16:17]
	flat_load_dwordx4 v[152:155], v[16:17] offset:32
	flat_load_dwordx4 v[148:151], v[16:17] offset:64
	flat_load_dwordx4 v[144:147], v[16:17] offset:96
	s_cmp_lt_u32 s95, 4
	s_cbranch_scc1 .Lmoba_early_done
	v_mov_b32_e32 v41, 0
	v_mov_b32_e32 v40, v224
	v_lshl_add_u64 v[40:41], v[40:41], 2, s[10:11]
	flat_load_dword v38, v[40:41]
	s_cmp_gt_u32 s65, 3
	s_cbranch_scc1 .Lmoba_early_done
	v_mov_b32_e32 v35, 0
	v_mov_b32_e32 v34, v224
	v_lshl_add_u64 v[34:35], s[8:9], 0, v[34:35]
	v_mov_b64_e32 v[36:37], s[28:29]
	s_movk_i32 s98, 0x3400
	v_mad_u64_u32 v[36:37], s[100:101], v34, s98, v[36:37]
	v_mad_i32_i24 v37, v35, s98, v37
	s_mov_b32 s63, s25
	v_lshl_add_u64 v[34:35], v[36:37], 0, s[62:63]
	flat_load_dwordx4 v[84:87], v[34:35]
	flat_load_dwordx4 v[88:91], v[34:35] offset:16
	flat_load_dwordx4 v[92:95], v[34:35] offset:32
	flat_load_dwordx4 v[96:99], v[34:35] offset:48
	flat_load_dwordx4 v[100:103], v[34:35] offset:64
	flat_load_dwordx4 v[104:107], v[34:35] offset:80
	flat_load_dwordx4 v[108:111], v[34:35] offset:96
	flat_load_dwordx4 v[112:115], v[34:35] offset:112
.Lmoba_early_done:
	s_add_u32 s14, s15, s62
	v_mul_u32_u24_e32 v16, 0x1a00, v239
	s_addc_u32 s15, s16, 0
	v_lshlrev_b32_e32 v222, 1, v16
	s_lshl_b32 s66, s65, 3
	v_lshl_add_u64 v[16:17], s[12:13], 0, v[222:223]
	s_ashr_i32 s67, s66, 31
	v_lshl_add_u64 v[80:81], s[66:67], 1, v[16:17]
	s_lshl_b32 s12, s65, 4
	v_bfe_u32 v16, v224, 2, 4
	v_and_or_b32 v16, s12, 48, v16
	s_ashr_i32 s12, s93, 3
	s_and_b32 s68, s12, 0xffffffe0
	v_mul_u32_u24_e32 v16, 0x1a00, v16
	s_ashr_i32 s69, s68, 31
	s_lshl_b32 s24, s65, 10
	v_lshlrev_b32_e32 v212, 1, v16
	v_mov_b32_e32 v213, v223
	v_lshlrev_b32_e32 v242, 3, v224
	s_cmp_lg_u32 0, -1
	v_lshl_add_u64 v[16:17], s[14:15], 0, v[212:213]
	v_and_b32_e32 v241, 24, v242
	s_cselect_b32 s12, 0, 0
	v_lshl_add_u64 v[16:17], s[68:69], 1, v[16:17]
	v_lshlrev_b32_e32 v18, 1, v241
	v_mov_b32_e32 v19, v223
	s_add_i32 s91, s24, s12
	s_mov_b32 s12, m0
	s_mov_b32 m0, s91
	s_nop 0
	global_load_lds_dwordx4 v[80:81], off
	s_mov_b32 m0, s12
	v_lshl_add_u64 v[82:83], v[16:17], 0, v[18:19]
	s_add_i32 s71, s91, 0x6000
	s_mov_b32 s12, m0
	s_mov_b32 m0, s71
	s_nop 0
	global_load_lds_dwordx4 v[82:83], off
	s_mov_b32 m0, s12
	v_lshl_add_u64 v[16:17], v[80:81], 0, s[34:35]
	s_add_i32 s12, s91, 0x2000
	s_mov_b32 s13, m0
	s_mov_b32 m0, s12
	s_nop 0
	global_load_lds_dwordx4 v[16:17], off
	s_mov_b32 m0, s13
	v_mov_b64_e32 v[30:31], v[14:15]
	v_mov_b64_e32 v[28:29], v[12:13]
	v_mov_b64_e32 v[26:27], v[10:11]
	v_mov_b64_e32 v[24:25], v[8:9]
	v_mov_b64_e32 v[22:23], v[6:7]
	v_mov_b64_e32 v[20:21], v[4:5]
	v_mov_b64_e32 v[18:19], v[2:3]
	v_mov_b64_e32 v[16:17], v[0:1]
	v_lshl_add_u64 v[32:33], v[80:81], 0, s[36:37]
	v_ashrrev_i32_e32 v225, 31, v224
	s_add_i32 s12, s91, 0x4000
	s_mov_b32 s13, m0
	s_mov_b32 m0, s12
	s_nop 0
	global_load_lds_dwordx4 v[32:33], off
	s_mov_b32 m0, s13
	s_cmp_lt_u32 s95, 4
	s_cbranch_scc1 .LBB0_898
	v_lshl_add_u32 v33, v224, 2, 0
	v_add_u32_e32 v33, 0x15000, v33
	s_movk_i32 s10, 0x100
	v_cmp_gt_i32_e32 vcc, s10, v224
	s_waitcnt vmcnt(4) lgkmcnt(0)
	ds_write_b32 v33, v38
	s_waitcnt vmcnt(4) lgkmcnt(0)
	s_barrier
	s_and_saveexec_b64 s[72:73], vcc
	s_cbranch_execz .LBB0_898
	s_lshl_b32 s10, -1, s95
	s_not_b32 s10, s10
	s_cmp_lt_u32 s95, 4
	v_mov_b32_e32 v32, s10
	s_cbranch_scc1 .LBB0_897
; template<int THRL,int MODE,int DM,bool DRY=false> __device__ __forceinline__ void attn_unit(int b,int h,int qb,const bf16*Q,const bf16*__restrict__ K,const bf16*__restrict__ V,bf16*O,const bf16*__restrict__ Z,const float*__restrict__ XP,const int*__restrict__ TS,volatile unsigned*lw,unsigned nxt,cha ...
;     ...
;       if(qb>3){ const bf16*qp=Q+(rowbase+q0+tid)*DM+h*D; float g[8];
;         _Pragma("unroll") for(int n=0;n<8;++n)g[n]=0.f;
;         _Pragma("unroll") for(int c=0;c<8;++c){ const bf16x8 qv=*reinterpret_cast<const bf16x8*>(qp+c*8);
;           _Pragma("unroll") for(int j=0;j<8;++j){ const float qf=__uint_as_float(((unsigned)(unsigned short)qv[j])<<16);
;             _Pragma("unroll") for(int n=0;n<8;++n)g[n]+=qf*kbs[n*64+c*8+j]; } }
	s_mov_b32 s10, 0xff800000
	s_cmp_lg_u32 s95, 4
	s_cselect_b64 s[74:75], -1, 0
	v_mov_b32_e32 v74, 0x15000
	v_mov_b32_e32 v32, 0
	v_mov_b32_e32 v33, 0
	v_mov_b32_e32 v34, 0
	v_mov_b32_e32 v35, 0
	v_mov_b32_e32 v36, 0
	v_mov_b32_e32 v37, 0
	v_mov_b32_e32 v38, 0
	v_mov_b32_e32 v39, 0
	ds_read_b128 v[42:45], v74 offset:0
	ds_read_b128 v[46:49], v74 offset:256
	ds_read_b128 v[50:53], v74 offset:512
	ds_read_b128 v[54:57], v74 offset:768
	ds_read_b128 v[58:61], v74 offset:1024
	ds_read_b128 v[62:65], v74 offset:1280
	ds_read_b128 v[66:69], v74 offset:1536
	ds_read_b128 v[70:73], v74 offset:1792
	s_waitcnt vmcnt(4) lgkmcnt(0)
	ds_read_b128 v[116:119], v74 offset:16
	ds_read_b128 v[120:123], v74 offset:272
	ds_read_b128 v[124:127], v74 offset:528
	ds_read_b128 v[128:131], v74 offset:784
	ds_read_b128 v[132:135], v74 offset:1040
	ds_read_b128 v[136:139], v74 offset:1296
	ds_read_b128 v[140:143], v74 offset:1552
	ds_read_b128 v[76:79], v74 offset:1808
	s_waitcnt lgkmcnt(8)
	v_lshlrev_b32_e32 v40, 16, v84
	v_fmac_f32_e32 v39, v42, v40
	v_fmac_f32_e32 v38, v46, v40
	v_fmac_f32_e32 v37, v50, v40
	v_fmac_f32_e32 v36, v54, v40
	v_fmac_f32_e32 v35, v58, v40
	v_fmac_f32_e32 v34, v62, v40
	v_fmac_f32_e32 v33, v66, v40
	v_fmac_f32_e32 v32, v70, v40
	v_and_b32_e32 v41, 0xffff0000, v84
	v_fmac_f32_e32 v39, v43, v41
	v_fmac_f32_e32 v38, v47, v41
	v_fmac_f32_e32 v37, v51, v41
	v_fmac_f32_e32 v36, v55, v41
	v_fmac_f32_e32 v35, v59, v41
	v_fmac_f32_e32 v34, v63, v41
	v_fmac_f32_e32 v33, v67, v41
	v_fmac_f32_e32 v32, v71, v41
	v_lshlrev_b32_e32 v40, 16, v85
	v_fmac_f32_e32 v39, v44, v40
	v_fmac_f32_e32 v38, v48, v40
	v_fmac_f32_e32 v37, v52, v40
	v_fmac_f32_e32 v36, v56, v40
	v_fmac_f32_e32 v35, v60, v40
	v_fmac_f32_e32 v34, v64, v40
	v_fmac_f32_e32 v33, v68, v40
	v_fmac_f32_e32 v32, v72, v40
	v_and_b32_e32 v41, 0xffff0000, v85
	v_fmac_f32_e32 v39, v45, v41
	v_fmac_f32_e32 v38, v49, v41
	v_fmac_f32_e32 v37, v53, v41
	v_fmac_f32_e32 v36, v57, v41
	v_fmac_f32_e32 v35, v61, v41
	v_fmac_f32_e32 v34, v65, v41
	v_fmac_f32_e32 v33, v69, v41
	v_fmac_f32_e32 v32, v73, v41
	ds_read_b128 v[42:45], v74 offset:32
	ds_read_b128 v[46:49], v74 offset:288
	ds_read_b128 v[50:53], v74 offset:544
	ds_read_b128 v[54:57], v74 offset:800
	ds_read_b128 v[58:61], v74 offset:1056
	ds_read_b128 v[62:65], v74 offset:1312
	ds_read_b128 v[66:69], v74 offset:1568
	ds_read_b128 v[70:73], v74 offset:1824
	s_waitcnt lgkmcnt(8)
	v_lshlrev_b32_e32 v40, 16, v86
	v_fmac_f32_e32 v39, v116, v40
	v_fmac_f32_e32 v38, v120, v40
	v_fmac_f32_e32 v37, v124, v40
	v_fmac_f32_e32 v36, v128, v40
	v_fmac_f32_e32 v35, v132, v40
	v_fmac_f32_e32 v34, v136, v40
	v_fmac_f32_e32 v33, v140, v40
	v_fmac_f32_e32 v32, v76, v40
	v_and_b32_e32 v41, 0xffff0000, v86
	v_fmac_f32_e32 v39, v117, v41
	v_fmac_f32_e32 v38, v121, v41
	v_fmac_f32_e32 v37, v125, v41
	v_fmac_f32_e32 v36, v129, v41
	v_fmac_f32_e32 v35, v133, v41
	v_fmac_f32_e32 v34, v137, v41
	v_fmac_f32_e32 v33, v141, v41
	v_fmac_f32_e32 v32, v77, v41
	v_lshlrev_b32_e32 v40, 16, v87
	v_fmac_f32_e32 v39, v118, v40
	v_fmac_f32_e32 v38, v122, v40
	v_fmac_f32_e32 v37, v126, v40
	v_fmac_f32_e32 v36, v130, v40
	v_fmac_f32_e32 v35, v134, v40
	v_fmac_f32_e32 v34, v138, v40
	v_fmac_f32_e32 v33, v142, v40
	v_fmac_f32_e32 v32, v78, v40
	v_and_b32_e32 v41, 0xffff0000, v87
	v_fmac_f32_e32 v39, v119, v41
	v_fmac_f32_e32 v38, v123, v41
	v_fmac_f32_e32 v37, v127, v41
	v_fmac_f32_e32 v36, v131, v41
	v_fmac_f32_e32 v35, v135, v41
	v_fmac_f32_e32 v34, v139, v41
	v_fmac_f32_e32 v33, v143, v41
	v_fmac_f32_e32 v32, v79, v41
	ds_read_b128 v[116:119], v74 offset:48
	ds_read_b128 v[120:123], v74 offset:304
	ds_read_b128 v[124:127], v74 offset:560
	ds_read_b128 v[128:131], v74 offset:816
	ds_read_b128 v[132:135], v74 offset:1072
	ds_read_b128 v[136:139], v74 offset:1328
	ds_read_b128 v[140:143], v74 offset:1584
	ds_read_b128 v[76:79], v74 offset:1840
	s_waitcnt lgkmcnt(8)
	v_lshlrev_b32_e32 v40, 16, v88
	v_fmac_f32_e32 v39, v42, v40
	v_fmac_f32_e32 v38, v46, v40
	v_fmac_f32_e32 v37, v50, v40
	v_fmac_f32_e32 v36, v54, v40
	v_fmac_f32_e32 v35, v58, v40
	v_fmac_f32_e32 v34, v62, v40
	v_fmac_f32_e32 v33, v66, v40
	v_fmac_f32_e32 v32, v70, v40
	v_and_b32_e32 v41, 0xffff0000, v88
	v_fmac_f32_e32 v39, v43, v41
	v_fmac_f32_e32 v38, v47, v41
	v_fmac_f32_e32 v37, v51, v41
	v_fmac_f32_e32 v36, v55, v41
	v_fmac_f32_e32 v35, v59, v41
	v_fmac_f32_e32 v34, v63, v41
	v_fmac_f32_e32 v33, v67, v41
	v_fmac_f32_e32 v32, v71, v41
	v_lshlrev_b32_e32 v40, 16, v89
	v_fmac_f32_e32 v39, v44, v40
	v_fmac_f32_e32 v38, v48, v40
	v_fmac_f32_e32 v37, v52, v40
	v_fmac_f32_e32 v36, v56, v40
	v_fmac_f32_e32 v35, v60, v40
	v_fmac_f32_e32 v34, v64, v40
	v_fmac_f32_e32 v33, v68, v40
	v_fmac_f32_e32 v32, v72, v40
	v_and_b32_e32 v41, 0xffff0000, v89
	v_fmac_f32_e32 v39, v45, v41
	v_fmac_f32_e32 v38, v49, v41
	v_fmac_f32_e32 v37, v53, v41
	v_fmac_f32_e32 v36, v57, v41
	v_fmac_f32_e32 v35, v61, v41
	v_fmac_f32_e32 v34, v65, v41
	v_fmac_f32_e32 v33, v69, v41
	v_fmac_f32_e32 v32, v73, v41
	ds_read_b128 v[42:45], v74 offset:64
	ds_read_b128 v[46:49], v74 offset:320
	ds_read_b128 v[50:53], v74 offset:576
	ds_read_b128 v[54:57], v74 offset:832
	ds_read_b128 v[58:61], v74 offset:1088
	ds_read_b128 v[62:65], v74 offset:1344
	ds_read_b128 v[66:69], v74 offset:1600
	ds_read_b128 v[70:73], v74 offset:1856
	s_waitcnt lgkmcnt(8)
; template<int THRL,int MODE,int DM,bool DRY=false> __device__ __forceinline__ void attn_unit(int b,int h,int qb,const bf16*Q,const bf16*__restrict__ K,const bf16*__restrict__ V,bf16*O,const bf16*__restrict__ Z,const float*__restrict__ XP,const int*__restrict__ TS,volatile unsigned*lw,unsigned nxt,cha ...
;     ...
;         _Pragma("unroll") for(int c=0;c<8;++c){ const bf16x8 qv=*reinterpret_cast<const bf16x8*>(qp+c*8);
;           _Pragma("unroll") for(int j=0;j<8;++j){ const float qf=__uint_as_float(((unsigned)(unsigned short)qv[j])<<16);
;             _Pragma("unroll") for(int n=0;n<8;++n)g[n]+=qf*kbs[n*64+c*8+j]; } }
	v_lshlrev_b32_e32 v40, 16, v90
	v_fmac_f32_e32 v39, v116, v40
	v_fmac_f32_e32 v38, v120, v40
	v_fmac_f32_e32 v37, v124, v40
	v_fmac_f32_e32 v36, v128, v40
	v_fmac_f32_e32 v35, v132, v40
	v_fmac_f32_e32 v34, v136, v40
	v_fmac_f32_e32 v33, v140, v40
	v_fmac_f32_e32 v32, v76, v40
	v_and_b32_e32 v41, 0xffff0000, v90
	v_fmac_f32_e32 v39, v117, v41
	v_fmac_f32_e32 v38, v121, v41
	v_fmac_f32_e32 v37, v125, v41
	v_fmac_f32_e32 v36, v129, v41
	v_fmac_f32_e32 v35, v133, v41
	v_fmac_f32_e32 v34, v137, v41
	v_fmac_f32_e32 v33, v141, v41
	v_fmac_f32_e32 v32, v77, v41
	v_lshlrev_b32_e32 v40, 16, v91
	v_fmac_f32_e32 v39, v118, v40
	v_fmac_f32_e32 v38, v122, v40
	v_fmac_f32_e32 v37, v126, v40
	v_fmac_f32_e32 v36, v130, v40
	v_fmac_f32_e32 v35, v134, v40
	v_fmac_f32_e32 v34, v138, v40
	v_fmac_f32_e32 v33, v142, v40
	v_fmac_f32_e32 v32, v78, v40
	v_and_b32_e32 v41, 0xffff0000, v91
	v_fmac_f32_e32 v39, v119, v41
	v_fmac_f32_e32 v38, v123, v41
	v_fmac_f32_e32 v37, v127, v41
	v_fmac_f32_e32 v36, v131, v41
	v_fmac_f32_e32 v35, v135, v41
	v_fmac_f32_e32 v34, v139, v41
	v_fmac_f32_e32 v33, v143, v41
	v_fmac_f32_e32 v32, v79, v41
	ds_read_b128 v[116:119], v74 offset:80
	ds_read_b128 v[120:123], v74 offset:336
	ds_read_b128 v[124:127], v74 offset:592
	ds_read_b128 v[128:131], v74 offset:848
	ds_read_b128 v[132:135], v74 offset:1104
	ds_read_b128 v[136:139], v74 offset:1360
	ds_read_b128 v[140:143], v74 offset:1616
	ds_read_b128 v[76:79], v74 offset:1872
	s_waitcnt lgkmcnt(8)
	v_lshlrev_b32_e32 v40, 16, v92
	v_fmac_f32_e32 v39, v42, v40
	v_fmac_f32_e32 v38, v46, v40
	v_fmac_f32_e32 v37, v50, v40
	v_fmac_f32_e32 v36, v54, v40
	v_fmac_f32_e32 v35, v58, v40
	v_fmac_f32_e32 v34, v62, v40
	v_fmac_f32_e32 v33, v66, v40
	v_fmac_f32_e32 v32, v70, v40
	v_and_b32_e32 v41, 0xffff0000, v92
	v_fmac_f32_e32 v39, v43, v41
	v_fmac_f32_e32 v38, v47, v41
	v_fmac_f32_e32 v37, v51, v41
	v_fmac_f32_e32 v36, v55, v41
	v_fmac_f32_e32 v35, v59, v41
	v_fmac_f32_e32 v34, v63, v41
	v_fmac_f32_e32 v33, v67, v41
	v_fmac_f32_e32 v32, v71, v41
	v_lshlrev_b32_e32 v40, 16, v93
	v_fmac_f32_e32 v39, v44, v40
	v_fmac_f32_e32 v38, v48, v40
	v_fmac_f32_e32 v37, v52, v40
	v_fmac_f32_e32 v36, v56, v40
	v_fmac_f32_e32 v35, v60, v40
	v_fmac_f32_e32 v34, v64, v40
	v_fmac_f32_e32 v33, v68, v40
	v_fmac_f32_e32 v32, v72, v40
	v_and_b32_e32 v41, 0xffff0000, v93
	v_fmac_f32_e32 v39, v45, v41
	v_fmac_f32_e32 v38, v49, v41
	v_fmac_f32_e32 v37, v53, v41
	v_fmac_f32_e32 v36, v57, v41
	v_fmac_f32_e32 v35, v61, v41
	v_fmac_f32_e32 v34, v65, v41
	v_fmac_f32_e32 v33, v69, v41
	v_fmac_f32_e32 v32, v73, v41
	ds_read_b128 v[42:45], v74 offset:96
	ds_read_b128 v[46:49], v74 offset:352
	ds_read_b128 v[50:53], v74 offset:608
	ds_read_b128 v[54:57], v74 offset:864
	ds_read_b128 v[58:61], v74 offset:1120
	ds_read_b128 v[62:65], v74 offset:1376
	ds_read_b128 v[66:69], v74 offset:1632
	ds_read_b128 v[70:73], v74 offset:1888
	s_waitcnt lgkmcnt(8)
	v_lshlrev_b32_e32 v40, 16, v94
	v_fmac_f32_e32 v39, v116, v40
	v_fmac_f32_e32 v38, v120, v40
	v_fmac_f32_e32 v37, v124, v40
	v_fmac_f32_e32 v36, v128, v40
	v_fmac_f32_e32 v35, v132, v40
	v_fmac_f32_e32 v34, v136, v40
	v_fmac_f32_e32 v33, v140, v40
	v_fmac_f32_e32 v32, v76, v40
	v_and_b32_e32 v41, 0xffff0000, v94
	v_fmac_f32_e32 v39, v117, v41
	v_fmac_f32_e32 v38, v121, v41
	v_fmac_f32_e32 v37, v125, v41
	v_fmac_f32_e32 v36, v129, v41
	v_fmac_f32_e32 v35, v133, v41
	v_fmac_f32_e32 v34, v137, v41
	v_fmac_f32_e32 v33, v141, v41
	v_fmac_f32_e32 v32, v77, v41
	v_lshlrev_b32_e32 v40, 16, v95
	v_fmac_f32_e32 v39, v118, v40
	v_fmac_f32_e32 v38, v122, v40
	v_fmac_f32_e32 v37, v126, v40
	v_fmac_f32_e32 v36, v130, v40
	v_fmac_f32_e32 v35, v134, v40
	v_fmac_f32_e32 v34, v138, v40
	v_fmac_f32_e32 v33, v142, v40
	v_fmac_f32_e32 v32, v78, v40
	v_and_b32_e32 v41, 0xffff0000, v95
	v_fmac_f32_e32 v39, v119, v41
	v_fmac_f32_e32 v38, v123, v41
	v_fmac_f32_e32 v37, v127, v41
	v_fmac_f32_e32 v36, v131, v41
	v_fmac_f32_e32 v35, v135, v41
	v_fmac_f32_e32 v34, v139, v41
	v_fmac_f32_e32 v33, v143, v41
	v_fmac_f32_e32 v32, v79, v41
	ds_read_b128 v[116:119], v74 offset:112
	ds_read_b128 v[120:123], v74 offset:368
	ds_read_b128 v[124:127], v74 offset:624
	ds_read_b128 v[128:131], v74 offset:880
	ds_read_b128 v[132:135], v74 offset:1136
	ds_read_b128 v[136:139], v74 offset:1392
	ds_read_b128 v[140:143], v74 offset:1648
	ds_read_b128 v[76:79], v74 offset:1904
	s_waitcnt lgkmcnt(8)
	v_lshlrev_b32_e32 v40, 16, v96
	v_fmac_f32_e32 v39, v42, v40
	v_fmac_f32_e32 v38, v46, v40
	v_fmac_f32_e32 v37, v50, v40
	v_fmac_f32_e32 v36, v54, v40
	v_fmac_f32_e32 v35, v58, v40
	v_fmac_f32_e32 v34, v62, v40
	v_fmac_f32_e32 v33, v66, v40
	v_fmac_f32_e32 v32, v70, v40
	v_and_b32_e32 v41, 0xffff0000, v96
	v_fmac_f32_e32 v39, v43, v41
	v_fmac_f32_e32 v38, v47, v41
	v_fmac_f32_e32 v37, v51, v41
	v_fmac_f32_e32 v36, v55, v41
	v_fmac_f32_e32 v35, v59, v41
	v_fmac_f32_e32 v34, v63, v41
	v_fmac_f32_e32 v33, v67, v41
	v_fmac_f32_e32 v32, v71, v41
	v_lshlrev_b32_e32 v40, 16, v97
	v_fmac_f32_e32 v39, v44, v40
	v_fmac_f32_e32 v38, v48, v40
	v_fmac_f32_e32 v37, v52, v40
	v_fmac_f32_e32 v36, v56, v40
	v_fmac_f32_e32 v35, v60, v40
	v_fmac_f32_e32 v34, v64, v40
	v_fmac_f32_e32 v33, v68, v40
	v_fmac_f32_e32 v32, v72, v40
	v_and_b32_e32 v41, 0xffff0000, v97
	v_fmac_f32_e32 v39, v45, v41
	v_fmac_f32_e32 v38, v49, v41
	v_fmac_f32_e32 v37, v53, v41
	v_fmac_f32_e32 v36, v57, v41
	v_fmac_f32_e32 v35, v61, v41
	v_fmac_f32_e32 v34, v65, v41
	v_fmac_f32_e32 v33, v69, v41
	v_fmac_f32_e32 v32, v73, v41
	ds_read_b128 v[42:45], v74 offset:128
	ds_read_b128 v[46:49], v74 offset:384
	ds_read_b128 v[50:53], v74 offset:640
	ds_read_b128 v[54:57], v74 offset:896
	ds_read_b128 v[58:61], v74 offset:1152
	ds_read_b128 v[62:65], v74 offset:1408
	ds_read_b128 v[66:69], v74 offset:1664
	ds_read_b128 v[70:73], v74 offset:1920
	s_waitcnt lgkmcnt(8)
; template<int THRL,int MODE,int DM,bool DRY=false> __device__ __forceinline__ void attn_unit(int b,int h,int qb,const bf16*Q,const bf16*__restrict__ K,const bf16*__restrict__ V,bf16*O,const bf16*__restrict__ Z,const float*__restrict__ XP,const int*__restrict__ TS,volatile unsigned*lw,unsigned nxt,cha ...
;     ...
;         _Pragma("unroll") for(int c=0;c<8;++c){ const bf16x8 qv=*reinterpret_cast<const bf16x8*>(qp+c*8);
;           _Pragma("unroll") for(int j=0;j<8;++j){ const float qf=__uint_as_float(((unsigned)(unsigned short)qv[j])<<16);
;             _Pragma("unroll") for(int n=0;n<8;++n)g[n]+=qf*kbs[n*64+c*8+j]; } }
	v_lshlrev_b32_e32 v40, 16, v98
	v_fmac_f32_e32 v39, v116, v40
	v_fmac_f32_e32 v38, v120, v40
	v_fmac_f32_e32 v37, v124, v40
	v_fmac_f32_e32 v36, v128, v40
	v_fmac_f32_e32 v35, v132, v40
	v_fmac_f32_e32 v34, v136, v40
	v_fmac_f32_e32 v33, v140, v40
	v_fmac_f32_e32 v32, v76, v40
	v_and_b32_e32 v41, 0xffff0000, v98
	v_fmac_f32_e32 v39, v117, v41
	v_fmac_f32_e32 v38, v121, v41
	v_fmac_f32_e32 v37, v125, v41
	v_fmac_f32_e32 v36, v129, v41
	v_fmac_f32_e32 v35, v133, v41
	v_fmac_f32_e32 v34, v137, v41
	v_fmac_f32_e32 v33, v141, v41
	v_fmac_f32_e32 v32, v77, v41
	v_lshlrev_b32_e32 v40, 16, v99
	v_fmac_f32_e32 v39, v118, v40
	v_fmac_f32_e32 v38, v122, v40
	v_fmac_f32_e32 v37, v126, v40
	v_fmac_f32_e32 v36, v130, v40
	v_fmac_f32_e32 v35, v134, v40
	v_fmac_f32_e32 v34, v138, v40
	v_fmac_f32_e32 v33, v142, v40
	v_fmac_f32_e32 v32, v78, v40
	v_and_b32_e32 v41, 0xffff0000, v99
	v_fmac_f32_e32 v39, v119, v41
	v_fmac_f32_e32 v38, v123, v41
	v_fmac_f32_e32 v37, v127, v41
	v_fmac_f32_e32 v36, v131, v41
	v_fmac_f32_e32 v35, v135, v41
	v_fmac_f32_e32 v34, v139, v41
	v_fmac_f32_e32 v33, v143, v41
	v_fmac_f32_e32 v32, v79, v41
	ds_read_b128 v[116:119], v74 offset:144
	ds_read_b128 v[120:123], v74 offset:400
	ds_read_b128 v[124:127], v74 offset:656
	ds_read_b128 v[128:131], v74 offset:912
	ds_read_b128 v[132:135], v74 offset:1168
	ds_read_b128 v[136:139], v74 offset:1424
	ds_read_b128 v[140:143], v74 offset:1680
	ds_read_b128 v[76:79], v74 offset:1936
	s_waitcnt lgkmcnt(8)
	v_lshlrev_b32_e32 v40, 16, v100
	v_fmac_f32_e32 v39, v42, v40
	v_fmac_f32_e32 v38, v46, v40
	v_fmac_f32_e32 v37, v50, v40
	v_fmac_f32_e32 v36, v54, v40
	v_fmac_f32_e32 v35, v58, v40
	v_fmac_f32_e32 v34, v62, v40
	v_fmac_f32_e32 v33, v66, v40
	v_fmac_f32_e32 v32, v70, v40
	v_and_b32_e32 v41, 0xffff0000, v100
	v_fmac_f32_e32 v39, v43, v41
	v_fmac_f32_e32 v38, v47, v41
	v_fmac_f32_e32 v37, v51, v41
	v_fmac_f32_e32 v36, v55, v41
	v_fmac_f32_e32 v35, v59, v41
	v_fmac_f32_e32 v34, v63, v41
	v_fmac_f32_e32 v33, v67, v41
	v_fmac_f32_e32 v32, v71, v41
	v_lshlrev_b32_e32 v40, 16, v101
	v_fmac_f32_e32 v39, v44, v40
	v_fmac_f32_e32 v38, v48, v40
	v_fmac_f32_e32 v37, v52, v40
	v_fmac_f32_e32 v36, v56, v40
	v_fmac_f32_e32 v35, v60, v40
	v_fmac_f32_e32 v34, v64, v40
	v_fmac_f32_e32 v33, v68, v40
	v_fmac_f32_e32 v32, v72, v40
	v_and_b32_e32 v41, 0xffff0000, v101
	v_fmac_f32_e32 v39, v45, v41
	v_fmac_f32_e32 v38, v49, v41
	v_fmac_f32_e32 v37, v53, v41
	v_fmac_f32_e32 v36, v57, v41
	v_fmac_f32_e32 v35, v61, v41
	v_fmac_f32_e32 v34, v65, v41
	v_fmac_f32_e32 v33, v69, v41
	v_fmac_f32_e32 v32, v73, v41
	ds_read_b128 v[42:45], v74 offset:160
	ds_read_b128 v[46:49], v74 offset:416
	ds_read_b128 v[50:53], v74 offset:672
	ds_read_b128 v[54:57], v74 offset:928
	ds_read_b128 v[58:61], v74 offset:1184
	ds_read_b128 v[62:65], v74 offset:1440
	ds_read_b128 v[66:69], v74 offset:1696
	ds_read_b128 v[70:73], v74 offset:1952
	s_waitcnt lgkmcnt(8)
	v_lshlrev_b32_e32 v40, 16, v102
	v_fmac_f32_e32 v39, v116, v40
	v_fmac_f32_e32 v38, v120, v40
	v_fmac_f32_e32 v37, v124, v40
	v_fmac_f32_e32 v36, v128, v40
	v_fmac_f32_e32 v35, v132, v40
	v_fmac_f32_e32 v34, v136, v40
	v_fmac_f32_e32 v33, v140, v40
	v_fmac_f32_e32 v32, v76, v40
	v_and_b32_e32 v41, 0xffff0000, v102
	v_fmac_f32_e32 v39, v117, v41
	v_fmac_f32_e32 v38, v121, v41
	v_fmac_f32_e32 v37, v125, v41
	v_fmac_f32_e32 v36, v129, v41
	v_fmac_f32_e32 v35, v133, v41
	v_fmac_f32_e32 v34, v137, v41
	v_fmac_f32_e32 v33, v141, v41
	v_fmac_f32_e32 v32, v77, v41
	v_lshlrev_b32_e32 v40, 16, v103
	v_fmac_f32_e32 v39, v118, v40
	v_fmac_f32_e32 v38, v122, v40
	v_fmac_f32_e32 v37, v126, v40
	v_fmac_f32_e32 v36, v130, v40
	v_fmac_f32_e32 v35, v134, v40
	v_fmac_f32_e32 v34, v138, v40
	v_fmac_f32_e32 v33, v142, v40
	v_fmac_f32_e32 v32, v78, v40
	v_and_b32_e32 v41, 0xffff0000, v103
	v_fmac_f32_e32 v39, v119, v41
	v_fmac_f32_e32 v38, v123, v41
	v_fmac_f32_e32 v37, v127, v41
	v_fmac_f32_e32 v36, v131, v41
	v_fmac_f32_e32 v35, v135, v41
	v_fmac_f32_e32 v34, v139, v41
	v_fmac_f32_e32 v33, v143, v41
	v_fmac_f32_e32 v32, v79, v41
	ds_read_b128 v[116:119], v74 offset:176
	ds_read_b128 v[120:123], v74 offset:432
	ds_read_b128 v[124:127], v74 offset:688
	ds_read_b128 v[128:131], v74 offset:944
	ds_read_b128 v[132:135], v74 offset:1200
	ds_read_b128 v[136:139], v74 offset:1456
	ds_read_b128 v[140:143], v74 offset:1712
	ds_read_b128 v[76:79], v74 offset:1968
	s_waitcnt lgkmcnt(8)
	v_lshlrev_b32_e32 v40, 16, v104
	v_fmac_f32_e32 v39, v42, v40
	v_fmac_f32_e32 v38, v46, v40
	v_fmac_f32_e32 v37, v50, v40
	v_fmac_f32_e32 v36, v54, v40
	v_fmac_f32_e32 v35, v58, v40
	v_fmac_f32_e32 v34, v62, v40
	v_fmac_f32_e32 v33, v66, v40
	v_fmac_f32_e32 v32, v70, v40
	v_and_b32_e32 v41, 0xffff0000, v104
	v_fmac_f32_e32 v39, v43, v41
	v_fmac_f32_e32 v38, v47, v41
	v_fmac_f32_e32 v37, v51, v41
	v_fmac_f32_e32 v36, v55, v41
	v_fmac_f32_e32 v35, v59, v41
	v_fmac_f32_e32 v34, v63, v41
	v_fmac_f32_e32 v33, v67, v41
	v_fmac_f32_e32 v32, v71, v41
	v_lshlrev_b32_e32 v40, 16, v105
	v_fmac_f32_e32 v39, v44, v40
	v_fmac_f32_e32 v38, v48, v40
	v_fmac_f32_e32 v37, v52, v40
	v_fmac_f32_e32 v36, v56, v40
	v_fmac_f32_e32 v35, v60, v40
	v_fmac_f32_e32 v34, v64, v40
	v_fmac_f32_e32 v33, v68, v40
	v_fmac_f32_e32 v32, v72, v40
	v_and_b32_e32 v41, 0xffff0000, v105
	v_fmac_f32_e32 v39, v45, v41
	v_fmac_f32_e32 v38, v49, v41
	v_fmac_f32_e32 v37, v53, v41
	v_fmac_f32_e32 v36, v57, v41
	v_fmac_f32_e32 v35, v61, v41
	v_fmac_f32_e32 v34, v65, v41
	v_fmac_f32_e32 v33, v69, v41
	v_fmac_f32_e32 v32, v73, v41
	ds_read_b128 v[42:45], v74 offset:192
	ds_read_b128 v[46:49], v74 offset:448
	ds_read_b128 v[50:53], v74 offset:704
	ds_read_b128 v[54:57], v74 offset:960
	ds_read_b128 v[58:61], v74 offset:1216
	ds_read_b128 v[62:65], v74 offset:1472
	ds_read_b128 v[66:69], v74 offset:1728
	ds_read_b128 v[70:73], v74 offset:1984
	s_waitcnt lgkmcnt(8)
; template<int THRL,int MODE,int DM,bool DRY=false> __device__ __forceinline__ void attn_unit(int b,int h,int qb,const bf16*Q,const bf16*__restrict__ K,const bf16*__restrict__ V,bf16*O,const bf16*__restrict__ Z,const float*__restrict__ XP,const int*__restrict__ TS,volatile unsigned*lw,unsigned nxt,cha ...
;     ...
;       if(qb>3){ const bf16*qp=Q+(rowbase+q0+tid)*DM+h*D; float g[8];
;         _Pragma("unroll") for(int n=0;n<8;++n)g[n]=0.f;
;         _Pragma("unroll") for(int c=0;c<8;++c){ const bf16x8 qv=*reinterpret_cast<const bf16x8*>(qp+c*8);
;           _Pragma("unroll") for(int j=0;j<8;++j){ const float qf=__uint_as_float(((unsigned)(unsigned short)qv[j])<<16);
;             _Pragma("unroll") for(int n=0;n<8;++n)g[n]+=qf*kbs[n*64+c*8+j]; } }
	v_lshlrev_b32_e32 v40, 16, v106
	v_fmac_f32_e32 v39, v116, v40
	v_fmac_f32_e32 v38, v120, v40
	v_fmac_f32_e32 v37, v124, v40
	v_fmac_f32_e32 v36, v128, v40
	v_fmac_f32_e32 v35, v132, v40
	v_fmac_f32_e32 v34, v136, v40
	v_fmac_f32_e32 v33, v140, v40
	v_fmac_f32_e32 v32, v76, v40
	v_and_b32_e32 v41, 0xffff0000, v106
	v_fmac_f32_e32 v39, v117, v41
	v_fmac_f32_e32 v38, v121, v41
	v_fmac_f32_e32 v37, v125, v41
	v_fmac_f32_e32 v36, v129, v41
	v_fmac_f32_e32 v35, v133, v41
	v_fmac_f32_e32 v34, v137, v41
	v_fmac_f32_e32 v33, v141, v41
	v_fmac_f32_e32 v32, v77, v41
	v_lshlrev_b32_e32 v40, 16, v107
	v_fmac_f32_e32 v39, v118, v40
	v_fmac_f32_e32 v38, v122, v40
	v_fmac_f32_e32 v37, v126, v40
	v_fmac_f32_e32 v36, v130, v40
	v_fmac_f32_e32 v35, v134, v40
	v_fmac_f32_e32 v34, v138, v40
	v_fmac_f32_e32 v33, v142, v40
	v_fmac_f32_e32 v32, v78, v40
	v_and_b32_e32 v41, 0xffff0000, v107
	v_fmac_f32_e32 v39, v119, v41
	v_fmac_f32_e32 v38, v123, v41
	v_fmac_f32_e32 v37, v127, v41
	v_fmac_f32_e32 v36, v131, v41
	v_fmac_f32_e32 v35, v135, v41
	v_fmac_f32_e32 v34, v139, v41
	v_fmac_f32_e32 v33, v143, v41
	v_fmac_f32_e32 v32, v79, v41
	ds_read_b128 v[116:119], v74 offset:208
	ds_read_b128 v[120:123], v74 offset:464
	ds_read_b128 v[124:127], v74 offset:720
	ds_read_b128 v[128:131], v74 offset:976
	ds_read_b128 v[132:135], v74 offset:1232
	ds_read_b128 v[136:139], v74 offset:1488
	ds_read_b128 v[140:143], v74 offset:1744
	ds_read_b128 v[76:79], v74 offset:2000
	s_waitcnt lgkmcnt(8)
	v_lshlrev_b32_e32 v40, 16, v108
	v_fmac_f32_e32 v39, v42, v40
	v_fmac_f32_e32 v38, v46, v40
	v_fmac_f32_e32 v37, v50, v40
	v_fmac_f32_e32 v36, v54, v40
	v_fmac_f32_e32 v35, v58, v40
	v_fmac_f32_e32 v34, v62, v40
	v_fmac_f32_e32 v33, v66, v40
	v_fmac_f32_e32 v32, v70, v40
	v_and_b32_e32 v41, 0xffff0000, v108
	v_fmac_f32_e32 v39, v43, v41
	v_fmac_f32_e32 v38, v47, v41
	v_fmac_f32_e32 v37, v51, v41
	v_fmac_f32_e32 v36, v55, v41
	v_fmac_f32_e32 v35, v59, v41
	v_fmac_f32_e32 v34, v63, v41
	v_fmac_f32_e32 v33, v67, v41
	v_fmac_f32_e32 v32, v71, v41
	v_lshlrev_b32_e32 v40, 16, v109
	v_fmac_f32_e32 v39, v44, v40
	v_fmac_f32_e32 v38, v48, v40
	v_fmac_f32_e32 v37, v52, v40
	v_fmac_f32_e32 v36, v56, v40
	v_fmac_f32_e32 v35, v60, v40
	v_fmac_f32_e32 v34, v64, v40
	v_fmac_f32_e32 v33, v68, v40
	v_fmac_f32_e32 v32, v72, v40
	v_and_b32_e32 v41, 0xffff0000, v109
	v_fmac_f32_e32 v39, v45, v41
	v_fmac_f32_e32 v38, v49, v41
	v_fmac_f32_e32 v37, v53, v41
	v_fmac_f32_e32 v36, v57, v41
	v_fmac_f32_e32 v35, v61, v41
	v_fmac_f32_e32 v34, v65, v41
	v_fmac_f32_e32 v33, v69, v41
	v_fmac_f32_e32 v32, v73, v41
	ds_read_b128 v[42:45], v74 offset:224
	ds_read_b128 v[46:49], v74 offset:480
	ds_read_b128 v[50:53], v74 offset:736
	ds_read_b128 v[54:57], v74 offset:992
	ds_read_b128 v[58:61], v74 offset:1248
	ds_read_b128 v[62:65], v74 offset:1504
	ds_read_b128 v[66:69], v74 offset:1760
	ds_read_b128 v[70:73], v74 offset:2016
	s_waitcnt lgkmcnt(8)
	v_lshlrev_b32_e32 v40, 16, v110
	v_fmac_f32_e32 v39, v116, v40
	v_fmac_f32_e32 v38, v120, v40
	v_fmac_f32_e32 v37, v124, v40
	v_fmac_f32_e32 v36, v128, v40
	v_fmac_f32_e32 v35, v132, v40
	v_fmac_f32_e32 v34, v136, v40
	v_fmac_f32_e32 v33, v140, v40
	v_fmac_f32_e32 v32, v76, v40
	v_and_b32_e32 v41, 0xffff0000, v110
	v_fmac_f32_e32 v39, v117, v41
	v_fmac_f32_e32 v38, v121, v41
	v_fmac_f32_e32 v37, v125, v41
	v_fmac_f32_e32 v36, v129, v41
	v_fmac_f32_e32 v35, v133, v41
	v_fmac_f32_e32 v34, v137, v41
	v_fmac_f32_e32 v33, v141, v41
	v_fmac_f32_e32 v32, v77, v41
	v_lshlrev_b32_e32 v40, 16, v111
	v_fmac_f32_e32 v39, v118, v40
	v_fmac_f32_e32 v38, v122, v40
	v_fmac_f32_e32 v37, v126, v40
	v_fmac_f32_e32 v36, v130, v40
	v_fmac_f32_e32 v35, v134, v40
	v_fmac_f32_e32 v34, v138, v40
	v_fmac_f32_e32 v33, v142, v40
	v_fmac_f32_e32 v32, v78, v40
	v_and_b32_e32 v41, 0xffff0000, v111
	v_fmac_f32_e32 v39, v119, v41
	v_fmac_f32_e32 v38, v123, v41
	v_fmac_f32_e32 v37, v127, v41
	v_fmac_f32_e32 v36, v131, v41
	v_fmac_f32_e32 v35, v135, v41
	v_fmac_f32_e32 v34, v139, v41
	v_fmac_f32_e32 v33, v143, v41
	v_fmac_f32_e32 v32, v79, v41
	ds_read_b128 v[116:119], v74 offset:240
	ds_read_b128 v[120:123], v74 offset:496
	ds_read_b128 v[124:127], v74 offset:752
	ds_read_b128 v[128:131], v74 offset:1008
	ds_read_b128 v[132:135], v74 offset:1264
	ds_read_b128 v[136:139], v74 offset:1520
	ds_read_b128 v[140:143], v74 offset:1776
	ds_read_b128 v[76:79], v74 offset:2032
	s_waitcnt lgkmcnt(8)
	v_lshlrev_b32_e32 v40, 16, v112
	v_fmac_f32_e32 v39, v42, v40
	v_fmac_f32_e32 v38, v46, v40
	v_fmac_f32_e32 v37, v50, v40
	v_fmac_f32_e32 v36, v54, v40
	v_fmac_f32_e32 v35, v58, v40
	v_fmac_f32_e32 v34, v62, v40
	v_fmac_f32_e32 v33, v66, v40
	v_fmac_f32_e32 v32, v70, v40
	v_and_b32_e32 v41, 0xffff0000, v112
	v_fmac_f32_e32 v39, v43, v41
	v_fmac_f32_e32 v38, v47, v41
	v_fmac_f32_e32 v37, v51, v41
	v_fmac_f32_e32 v36, v55, v41
	v_fmac_f32_e32 v35, v59, v41
	v_fmac_f32_e32 v34, v63, v41
	v_fmac_f32_e32 v33, v67, v41
	v_fmac_f32_e32 v32, v71, v41
	v_lshlrev_b32_e32 v40, 16, v113
	v_fmac_f32_e32 v39, v44, v40
	v_fmac_f32_e32 v38, v48, v40
	v_fmac_f32_e32 v37, v52, v40
	v_fmac_f32_e32 v36, v56, v40
	v_fmac_f32_e32 v35, v60, v40
	v_fmac_f32_e32 v34, v64, v40
	v_fmac_f32_e32 v33, v68, v40
	v_fmac_f32_e32 v32, v72, v40
	v_and_b32_e32 v41, 0xffff0000, v113
	v_fmac_f32_e32 v39, v45, v41
	v_fmac_f32_e32 v38, v49, v41
	v_fmac_f32_e32 v37, v53, v41
	v_fmac_f32_e32 v36, v57, v41
	v_fmac_f32_e32 v35, v61, v41
	v_fmac_f32_e32 v34, v65, v41
	v_fmac_f32_e32 v33, v69, v41
	v_fmac_f32_e32 v32, v73, v41
	s_waitcnt lgkmcnt(0)
; template<int THRL,int MODE,int DM,bool DRY=false> __device__ __forceinline__ void attn_unit(int b,int h,int qb,const bf16*Q,const bf16*__restrict__ K,const bf16*__restrict__ V,bf16*O,const bf16*__restrict__ Z,const float*__restrict__ XP,const int*__restrict__ TS,volatile unsigned*lw,unsigned nxt,cha ...
;     ...
;             _Pragma("unroll") for(int n=0;n<8;++n)g[n]+=qf*kbs[n*64+c*8+j]; } }
;         m=0u;
;         _Pragma("unroll") for(int it=0;it<3;++it){ float best=-INFINITY; int bi=0;
;           _Pragma("unroll") for(int n=0;n<8;++n){ const bool ok=(n<qb)&&!((m>>n)&1u)&&(g[n]>best); best=ok?g[n]:best; bi=ok?n:bi; }
;           m|=1u<<bi; } }
	v_lshlrev_b32_e32 v40, 16, v114
	v_fmac_f32_e32 v39, v116, v40
	v_fmac_f32_e32 v38, v120, v40
	v_fmac_f32_e32 v37, v124, v40
	v_fmac_f32_e32 v36, v128, v40
	v_fmac_f32_e32 v35, v132, v40
	v_fmac_f32_e32 v34, v136, v40
	v_fmac_f32_e32 v33, v140, v40
	v_fmac_f32_e32 v32, v76, v40
	v_and_b32_e32 v41, 0xffff0000, v114
	v_fmac_f32_e32 v39, v117, v41
	v_fmac_f32_e32 v38, v121, v41
	v_fmac_f32_e32 v37, v125, v41
	v_fmac_f32_e32 v36, v129, v41
	v_fmac_f32_e32 v35, v133, v41
	v_fmac_f32_e32 v34, v137, v41
	v_fmac_f32_e32 v33, v141, v41
	v_fmac_f32_e32 v32, v77, v41
	v_lshlrev_b32_e32 v40, 16, v115
	v_fmac_f32_e32 v39, v118, v40
	v_fmac_f32_e32 v38, v122, v40
	v_fmac_f32_e32 v37, v126, v40
	v_fmac_f32_e32 v36, v130, v40
	v_fmac_f32_e32 v35, v134, v40
	v_fmac_f32_e32 v34, v138, v40
	v_fmac_f32_e32 v33, v142, v40
	v_fmac_f32_e32 v32, v78, v40
	v_and_b32_e32 v41, 0xffff0000, v115
	v_fmac_f32_e32 v39, v119, v41
	v_fmac_f32_e32 v38, v123, v41
	v_fmac_f32_e32 v37, v127, v41
	v_fmac_f32_e32 v36, v131, v41
	v_fmac_f32_e32 v35, v135, v41
	v_fmac_f32_e32 v34, v139, v41
	v_fmac_f32_e32 v33, v143, v41
	v_fmac_f32_e32 v32, v79, v41
	v_cmp_lg_f32_e32 vcc, s10, v39
	s_nop 1
	v_cndmask_b32_e32 v40, v234, v39, vcc
	v_cmp_gt_f32_e32 vcc, v38, v40
	s_nop 1
	v_cndmask_b32_e32 v40, v40, v38, vcc
	v_cndmask_b32_e64 v41, 0, 1, vcc
	v_cmp_gt_f32_e32 vcc, v37, v40
	s_nop 1
	v_cndmask_b32_e32 v40, v40, v37, vcc
	v_cndmask_b32_e64 v41, v41, 2, vcc
	v_cmp_gt_f32_e32 vcc, v36, v40
	s_nop 1
	v_cndmask_b32_e32 v40, v40, v36, vcc
	v_cndmask_b32_e64 v41, v41, 3, vcc
	v_cmp_gt_f32_e32 vcc, v35, v40
	s_and_b64 vcc, s[74:75], vcc
	s_cmp_gt_u32 s95, 5
	v_cndmask_b32_e32 v40, v40, v35, vcc
	v_cndmask_b32_e64 v41, v41, 4, vcc
	s_cselect_b64 s[76:77], -1, 0
	v_cmp_gt_f32_e32 vcc, v34, v40
	s_and_b64 vcc, s[76:77], vcc
	s_cmp_lt_u32 s92, -7
	v_cndmask_b32_e32 v40, v40, v34, vcc
	v_cndmask_b32_e64 v41, v41, 5, vcc
	s_cselect_b64 s[78:79], -1, 0
	v_cmp_gt_f32_e32 vcc, v33, v40
	s_and_b64 vcc, s[78:79], vcc
	s_cmp_gt_u32 s95, 7
	v_cndmask_b32_e32 v40, v40, v33, vcc
	v_cndmask_b32_e64 v41, v41, 6, vcc
	s_cselect_b64 s[80:81], -1, 0
	v_cmp_gt_f32_e32 vcc, v32, v40
	s_and_b64 s[8:9], s[80:81], vcc
	v_cndmask_b32_e64 v40, v41, 7, s[8:9]
	v_cmp_eq_u32_e64 s[8:9], 0, v40
	v_cmp_nlg_f32_e32 vcc, s10, v39
	v_lshlrev_b32_e64 v41, v40, 1
	s_or_b64 s[8:9], s[8:9], vcc
	v_cndmask_b32_e64 v40, v39, v234, s[8:9]
	v_and_b32_e32 v42, 2, v41
	v_cmp_eq_u32_e64 s[8:9], 0, v42
	v_cmp_gt_f32_e64 s[10:11], v38, v40
	s_and_b64 s[8:9], s[8:9], s[10:11]
	v_cndmask_b32_e64 v40, v40, v38, s[8:9]
	v_and_b32_e32 v43, 4, v41
	v_cndmask_b32_e64 v42, 0, 1, s[8:9]
	v_cmp_eq_u32_e64 s[8:9], 0, v43
	v_cmp_gt_f32_e64 s[10:11], v37, v40
	s_and_b64 s[18:19], s[8:9], s[10:11]
	v_cndmask_b32_e64 v40, v40, v37, s[18:19]
	v_and_b32_e32 v43, 8, v41
	v_cmp_eq_u32_e64 s[8:9], 0, v43
	v_cmp_gt_f32_e64 s[10:11], v36, v40
	s_and_b64 s[16:17], s[8:9], s[10:11]
	v_and_b32_e32 v43, 16, v41
	v_cndmask_b32_e64 v40, v40, v36, s[16:17]
	v_cmp_eq_u32_e64 s[8:9], 0, v43
	s_and_b64 s[10:11], s[74:75], s[8:9]
	v_cmp_gt_f32_e64 s[8:9], v35, v40
	s_and_b64 s[14:15], s[10:11], s[8:9]
	v_and_b32_e32 v43, 32, v41
	v_cndmask_b32_e64 v40, v40, v35, s[14:15]
	v_cmp_eq_u32_e64 s[8:9], 0, v43
	s_and_b64 s[10:11], s[76:77], s[8:9]
	v_cmp_gt_f32_e64 s[8:9], v34, v40
	s_and_b64 s[12:13], s[10:11], s[8:9]
	v_and_b32_e32 v43, 64, v41
	v_cndmask_b32_e64 v40, v40, v34, s[12:13]
	v_cmp_eq_u32_e64 s[8:9], 0, v43
	s_and_b64 s[10:11], s[78:79], s[8:9]
	v_cmp_gt_f32_e64 s[8:9], v33, v40
	s_and_b64 s[10:11], s[10:11], s[8:9]
	v_and_b32_e32 v43, 0x80, v41
	v_cndmask_b32_e64 v40, v40, v33, s[10:11]
	v_cmp_eq_u32_e64 s[8:9], 0, v43
	s_and_b64 s[42:43], s[80:81], s[8:9]
	v_cmp_gt_f32_e64 s[8:9], v32, v40
	v_lshlrev_b32_e64 v40, v42, 1
	v_cndmask_b32_e64 v40, v40, 4, s[18:19]
	v_cndmask_b32_e64 v40, v40, 8, s[16:17]
	v_cndmask_b32_e64 v40, v40, 16, s[14:15]
	v_cndmask_b32_e64 v40, v40, 32, s[12:13]
	s_and_b64 s[8:9], s[42:43], s[8:9]
	v_cndmask_b32_e64 v40, v40, 64, s[10:11]
	v_cndmask_b32_e64 v40, v40, v235, s[8:9]
	v_or_b32_e32 v42, v40, v41
	v_and_b32_e32 v43, 1, v42
	v_cmp_eq_u32_e64 s[8:9], 1, v43
	s_or_b64 vcc, s[8:9], vcc
	v_cndmask_b32_e32 v39, v39, v234, vcc
	v_bitop3_b32 v43, v40, 2, v41 bitop3:0xc8
	v_cmp_eq_u32_e32 vcc, 0, v43
	v_cmp_gt_f32_e64 s[8:9], v38, v39
	s_and_b64 vcc, vcc, s[8:9]
	v_cndmask_b32_e32 v38, v39, v38, vcc
	v_bitop3_b32 v39, v40, 4, v41 bitop3:0xc8
	v_cndmask_b32_e64 v43, 0, 1, vcc
	v_cmp_eq_u32_e32 vcc, 0, v39
	v_cmp_gt_f32_e64 s[8:9], v37, v38
	s_and_b64 s[8:9], vcc, s[8:9]
	s_nop 0
	v_cndmask_b32_e64 v37, v38, v37, s[8:9]
	v_bitop3_b32 v38, v40, 8, v41 bitop3:0xc8
	v_cmp_eq_u32_e32 vcc, 0, v38
	v_cmp_gt_f32_e64 s[10:11], v36, v37
	s_and_b64 vcc, vcc, s[10:11]
	v_cndmask_b32_e32 v36, v37, v36, vcc
	v_bitop3_b32 v37, v40, 16, v41 bitop3:0xc8
	v_cmp_eq_u32_e64 s[10:11], 0, v37
	s_and_b64 s[12:13], s[74:75], s[10:11]
	v_cmp_gt_f32_e64 s[10:11], v35, v36
	s_and_b64 s[10:11], s[12:13], s[10:11]
	s_nop 0
	v_cndmask_b32_e64 v35, v36, v35, s[10:11]
	v_bitop3_b32 v36, v40, 32, v41 bitop3:0xc8
	v_cmp_eq_u32_e64 s[12:13], 0, v36
	s_and_b64 s[14:15], s[76:77], s[12:13]
	v_cmp_gt_f32_e64 s[12:13], v34, v35
	s_and_b64 s[12:13], s[14:15], s[12:13]
	s_nop 0
	v_cndmask_b32_e64 v34, v35, v34, s[12:13]
	v_bitop3_b32 v35, v40, 64, v41 bitop3:0xc8
	v_cmp_eq_u32_e64 s[14:15], 0, v35
	s_and_b64 s[16:17], s[78:79], s[14:15]
	v_cmp_gt_f32_e64 s[14:15], v33, v34
	s_and_b64 s[14:15], s[16:17], s[14:15]
	s_movk_i32 s16, 0x80
	v_cndmask_b32_e64 v33, v34, v33, s[14:15]
	v_bitop3_b32 v34, v40, s16, v41 bitop3:0xc8
	v_cmp_eq_u32_e64 s[16:17], 0, v34
	s_and_b64 s[18:19], s[80:81], s[16:17]
	v_cmp_gt_f32_e64 s[16:17], v32, v33
	v_lshlrev_b32_e64 v32, v43, 1
	v_cndmask_b32_e64 v32, v32, 4, s[8:9]
	v_cndmask_b32_e64 v32, v32, 8, vcc
	v_cndmask_b32_e64 v32, v32, 16, s[10:11]
	v_cndmask_b32_e64 v32, v32, 32, s[12:13]
	s_and_b64 s[16:17], s[18:19], s[16:17]
	v_cndmask_b32_e64 v32, v32, 64, s[14:15]
	v_cndmask_b32_e64 v32, v32, v235, s[16:17]
	v_readlane_b32 s78, v253, 1
	v_or_b32_e32 v32, v32, v42
	v_readlane_b32 s79, v253, 2

; template<int THRL,int MODE,int DM,bool DRY=false> __device__ __forceinline__ void attn_unit(int b,int h,int qb,const bf16*Q,const bf16*__restrict__ K,const bf16*__restrict__ V,bf16*O,const bf16*__restrict__ Z,const float*__restrict__ XP,const int*__restrict__ TS,volatile unsigned*lw,unsigned nxt,cha ...
;     ...
;       sm[tid]=m; }
;     asm volatile("s_waitcnt vmcnt(0) lgkmcnt(0)\n\ts_barrier":::"memory");
;     sel=sm[qrel];
.LBB0_898:
	s_or_b64 exec, exec, s[72:73]
	v_lshlrev_b32_e32 v32, 10, v238
	v_lshlrev_b32_e32 v33, 4, v237
	v_or_b32_e32 v246, s96, v237
	v_add3_u32 v248, 0, v32, v33
	v_lshl_add_u32 v32, v246, 2, 0
	s_cmp_lt_u32 s95, 4
	s_cbranch_scc1 .Lmoba_small_sel
	s_waitcnt vmcnt(4) lgkmcnt(0)
	s_barrier
	v_add_u32_e32 v32, 0x15800, v32
	ds_read_b32 v249, v32
	s_branch .Lmoba_sel_done
